# prep_dn rms reduction: the three xor-shuffle adds per group done with DPP (quad_perm / row_half_mirror) instead of ds_bpermute LDS round trips
# baseline (speedup 1.0000x reference)
; DI float siluf(float x) { return x / (1.f + __expf(-x)); }
; DI void prep_dn(const Params& p, int layer, int tile, char* lds) {
;     ...
;       for (int j = 0; j < 5; ++j) {
;         float x[8];
;         unpack8(xr[u][j], x);
;         const float4 w0 = *(const float4*)(cw + j * 768 + ch8 * 8), w1 = *(const float4*)(cw + j * 768 + ch8 * 8 + 4);
;         acc[0] += x[0] * w0.x; acc[1] += x[1] * w0.y; acc[2] += x[2] * w0.z; acc[3] += x[3] * w0.w;
;         acc[4] += x[4] * w1.x; acc[5] += x[5] * w1.y; acc[6] += x[6] * w1.z; acc[7] += x[7] * w1.w;
;       }
;       float ss = 0.f;
; #pragma unroll
;       for (int e = 0; e < 8; ++e) { acc[e] = siluf(acc[e]); ss += acc[e] * acc[e]; }
.LBB0_326:
	s_or_b64 exec, exec, s[0:1]
	v_lshl_add_u32 v98, v110, 2, s88
	ds_read_b128 v[86:89], v98
	ds_read_b128 v[82:85], v98 offset:16
	s_waitcnt vmcnt(0)
	v_lshlrev_b32_e32 v90, 16, v66
	v_and_b32_e32 v91, 0xffff0000, v66
	v_lshlrev_b32_e32 v94, 16, v62
	s_waitcnt lgkmcnt(1)
	v_pk_fma_f32 v[86:87], v[86:87], v[90:91], 0 op_sel_hi:[1,1,0]
	ds_read_b128 v[90:93], v98 offset:3072
	v_and_b32_e32 v95, 0xffff0000, v62
	ds_read_b128 v[128:131], v98 offset:9216
	ds_read_b128 v[132:135], v98 offset:12288
	s_waitcnt lgkmcnt(2)
	v_pk_fma_f32 v[86:87], v[90:91], v[94:95], v[86:87]
	ds_read_b128 v[94:97], v98 offset:6144
	v_lshlrev_b32_e32 v90, 16, v74
	v_and_b32_e32 v91, 0xffff0000, v74
	s_waitcnt lgkmcnt(0)
	v_pk_fma_f32 v[86:87], v[94:95], v[90:91], v[86:87]
	v_lshlrev_b32_e32 v90, 16, v70
	v_and_b32_e32 v91, 0xffff0000, v70
	v_pk_fma_f32 v[86:87], v[128:129], v[90:91], v[86:87]
	v_lshlrev_b32_e32 v90, 16, v78
	v_and_b32_e32 v91, 0xffff0000, v78
	v_pk_fma_f32 v[86:87], v[132:133], v[90:91], v[86:87]
	s_nop 0
	v_mul_f32_e32 v0, 0xbfb8aa3b, v86
	v_exp_f32_e32 v90, v0
	v_mul_f32_e32 v0, 0xbfb8aa3b, v87
	v_exp_f32_e32 v91, v0
	v_mov_b32_e32 v0, 1.0
	v_pk_add_f32 v[90:91], v[90:91], 1.0 op_sel_hi:[1,0]
	s_nop 0
	v_div_scale_f32 v62, s[0:1], v91, v91, v87
	v_rcp_f32_e32 v66, v62
	s_nop 0
	v_fma_f32 v70, -v62, v66, 1.0
	v_fmac_f32_e32 v66, v70, v66
	v_div_scale_f32 v70, vcc, v87, v91, v87
	v_mul_f32_e32 v74, v70, v66
	v_fma_f32 v78, -v62, v74, v70
	v_fmac_f32_e32 v74, v78, v66
	v_fma_f32 v62, -v62, v74, v70
	v_div_fmas_f32 v62, v62, v66, v74
	v_div_fixup_f32 v113, v62, v91, v87
	v_div_scale_f32 v62, s[0:1], v90, v90, v86
	v_rcp_f32_e32 v66, v62
	s_nop 0
	v_fma_f32 v70, -v62, v66, 1.0
	v_fmac_f32_e32 v66, v70, v66
	v_div_scale_f32 v70, vcc, v86, v90, v86
	v_mul_f32_e32 v74, v70, v66
	v_fma_f32 v78, -v62, v74, v70
	v_fmac_f32_e32 v74, v78, v66
	v_fma_f32 v62, -v62, v74, v70
	v_div_fmas_f32 v62, v62, v66, v74
	v_lshlrev_b32_e32 v66, 16, v67
	v_and_b32_e32 v67, 0xffff0000, v67
	v_div_fixup_f32 v112, v62, v90, v86
	v_pk_fma_f32 v[66:67], v[88:89], v[66:67], 0 op_sel_hi:[1,1,0]
	v_lshlrev_b32_e32 v62, 16, v63
	v_and_b32_e32 v63, 0xffff0000, v63
	v_pk_fma_f32 v[62:63], v[92:93], v[62:63], v[66:67]
	v_lshlrev_b32_e32 v66, 16, v75
	v_and_b32_e32 v67, 0xffff0000, v75
	v_pk_fma_f32 v[62:63], v[96:97], v[66:67], v[62:63]
	v_lshlrev_b32_e32 v66, 16, v71
	v_and_b32_e32 v67, 0xffff0000, v71
	v_pk_fma_f32 v[62:63], v[130:131], v[66:67], v[62:63]
	v_lshlrev_b32_e32 v66, 16, v79
	v_and_b32_e32 v67, 0xffff0000, v79
	v_pk_fma_f32 v[62:63], v[134:135], v[66:67], v[62:63]
	ds_read_b128 v[86:89], v98 offset:3088
	v_mul_f32_e32 v66, 0xbfb8aa3b, v62
	v_mul_f32_e32 v67, 0xbfb8aa3b, v63
	v_exp_f32_e32 v66, v66
	v_exp_f32_e32 v67, v67
	ds_read_b128 v[90:93], v98 offset:6160
	ds_read_b128 v[94:97], v98 offset:9232
	ds_read_b128 v[98:101], v98 offset:12304
	v_pk_add_f32 v[66:67], v[66:67], 1.0 op_sel_hi:[1,0]
	v_pk_mul_f32 v[114:115], v[112:113], v[112:113]
	v_div_scale_f32 v70, s[0:1], v67, v67, v63
	v_rcp_f32_e32 v71, v70
	s_nop 0
	v_fma_f32 v74, -v70, v71, 1.0
	v_fmac_f32_e32 v71, v74, v71
	v_div_scale_f32 v74, vcc, v63, v67, v63
	v_mul_f32_e32 v75, v74, v71
	v_fma_f32 v78, -v70, v75, v74
	v_fmac_f32_e32 v75, v78, v71
	v_fma_f32 v70, -v70, v75, v74
	v_div_fmas_f32 v70, v70, v71, v75
	v_div_fixup_f32 v63, v70, v67, v63
	v_div_scale_f32 v67, s[0:1], v66, v66, v62
	v_rcp_f32_e32 v70, v67
	s_nop 0
	v_fma_f32 v71, -v67, v70, 1.0
	v_fmac_f32_e32 v70, v71, v70
	v_div_scale_f32 v71, vcc, v62, v66, v62
	v_mul_f32_e32 v74, v71, v70
	v_fma_f32 v75, -v67, v74, v71
	v_fmac_f32_e32 v74, v75, v70
	v_fma_f32 v67, -v67, v74, v71
	v_div_fmas_f32 v67, v67, v70, v74
	v_lshlrev_b32_e32 v70, 16, v68
	v_and_b32_e32 v71, 0xffff0000, v68
	v_pk_fma_f32 v[70:71], v[82:83], v[70:71], 0 op_sel_hi:[1,1,0]
	v_lshlrev_b32_e32 v74, 16, v64
	v_and_b32_e32 v75, 0xffff0000, v64
	s_waitcnt lgkmcnt(3)
	v_pk_fma_f32 v[70:71], v[86:87], v[74:75], v[70:71]
	v_lshlrev_b32_e32 v74, 16, v76
	v_and_b32_e32 v75, 0xffff0000, v76
	s_waitcnt lgkmcnt(2)
	v_pk_fma_f32 v[70:71], v[90:91], v[74:75], v[70:71]
	v_lshlrev_b32_e32 v74, 16, v72
	v_and_b32_e32 v75, 0xffff0000, v72
	s_waitcnt lgkmcnt(1)
	v_pk_fma_f32 v[70:71], v[94:95], v[74:75], v[70:71]
	v_lshlrev_b32_e32 v74, 16, v80
	v_and_b32_e32 v75, 0xffff0000, v80
	s_waitcnt lgkmcnt(0)
; DI float siluf(float x) { return x / (1.f + __expf(-x)); }
; DI void prep_dn(const Params& p, int layer, int tile, char* lds) {
;     ...
;       float ss = 0.f;
; #pragma unroll
;       for (int e = 0; e < 8; ++e) { acc[e] = siluf(acc[e]); ss += acc[e] * acc[e]; }
;       ss += __shfl_xor(ss, 1); ss += __shfl_xor(ss, 2); ss += __shfl_xor(ss, 4);
;       const int grp = ch8 >> 3;
;       const float sc = grp < 8 ? rsqrtf(ss + 1e-6f) * (grp < 4 ? 0.125f : 1.f) : 1.f;
; #pragma unroll
;       for (int e = 0; e < 8; ++e) acc[e] *= sc;
;       *(u32x4*)(QKVB + (size_t)row * 768 + ch8 * 8) = pack8(acc);
	v_pk_fma_f32 v[70:71], v[98:99], v[74:75], v[70:71]
	v_div_fixup_f32 v62, v67, v66, v62
	v_mul_f32_e32 v64, 0xbfb8aa3b, v70
	v_exp_f32_e32 v74, v64
	v_mul_f32_e32 v64, 0xbfb8aa3b, v71
	v_exp_f32_e32 v75, v64
	v_pk_mul_f32 v[66:67], v[62:63], v[62:63]
	v_pk_add_f32 v[74:75], v[74:75], 1.0 op_sel_hi:[1,0]
	s_nop 0
	v_div_scale_f32 v64, s[0:1], v75, v75, v71
	v_rcp_f32_e32 v68, v64
	s_nop 0
	v_fma_f32 v72, -v64, v68, 1.0
	v_fmac_f32_e32 v68, v72, v68
	v_div_scale_f32 v72, vcc, v71, v75, v71
	v_mul_f32_e32 v76, v72, v68
	v_fma_f32 v78, -v64, v76, v72
	v_fmac_f32_e32 v76, v78, v68
	v_fma_f32 v64, -v64, v76, v72
	v_div_fmas_f32 v64, v64, v68, v76
	v_div_fixup_f32 v71, v64, v75, v71
	v_div_scale_f32 v64, s[0:1], v74, v74, v70
	v_rcp_f32_e32 v68, v64
	s_nop 0
	v_fma_f32 v72, -v64, v68, 1.0
	v_fmac_f32_e32 v68, v72, v68
	v_div_scale_f32 v72, vcc, v70, v74, v70
	v_mul_f32_e32 v75, v72, v68
	v_fma_f32 v76, -v64, v75, v72
	v_fmac_f32_e32 v75, v76, v68
	v_fma_f32 v64, -v64, v75, v72
	v_div_fmas_f32 v64, v64, v68, v75
	v_lshlrev_b32_e32 v68, 16, v69
	v_and_b32_e32 v69, 0xffff0000, v69
	v_div_fixup_f32 v70, v64, v74, v70
	v_pk_fma_f32 v[68:69], v[84:85], v[68:69], 0 op_sel_hi:[1,1,0]
	v_lshlrev_b32_e32 v64, 16, v65
	v_and_b32_e32 v65, 0xffff0000, v65
	v_pk_fma_f32 v[64:65], v[88:89], v[64:65], v[68:69]
	v_lshlrev_b32_e32 v68, 16, v77
	v_and_b32_e32 v69, 0xffff0000, v77
	v_pk_fma_f32 v[64:65], v[92:93], v[68:69], v[64:65]
	v_lshlrev_b32_e32 v68, 16, v73
	v_and_b32_e32 v69, 0xffff0000, v73
	v_pk_fma_f32 v[64:65], v[96:97], v[68:69], v[64:65]
	v_lshlrev_b32_e32 v68, 16, v81
	v_and_b32_e32 v69, 0xffff0000, v81
	v_pk_fma_f32 v[64:65], v[100:101], v[68:69], v[64:65]
	v_pk_mul_f32 v[74:75], v[70:71], v[70:71]
	v_mul_f32_e32 v68, 0xbfb8aa3b, v64
	v_mul_f32_e32 v69, 0xbfb8aa3b, v65
	v_exp_f32_e32 v68, v68
	v_exp_f32_e32 v69, v69
	s_nop 0
	v_pk_add_f32 v[68:69], v[68:69], 1.0 op_sel_hi:[1,0]
	s_nop 0
	v_div_scale_f32 v72, s[0:1], v69, v69, v65
	v_rcp_f32_e32 v73, v72
	s_nop 0
	v_fma_f32 v76, -v72, v73, 1.0
	v_fmac_f32_e32 v73, v76, v73
	v_div_scale_f32 v76, vcc, v65, v69, v65
	v_mul_f32_e32 v77, v76, v73
	v_fma_f32 v78, -v72, v77, v76
	v_fmac_f32_e32 v77, v78, v73
	v_fma_f32 v72, -v72, v77, v76
	v_div_fmas_f32 v72, v72, v73, v77
	v_div_fixup_f32 v65, v72, v69, v65
	v_div_scale_f32 v69, s[0:1], v68, v68, v64
	v_rcp_f32_e32 v72, v69
	s_nop 0
	v_fma_f32 v73, -v69, v72, 1.0
	v_fmac_f32_e32 v72, v73, v72
	v_div_scale_f32 v73, vcc, v64, v68, v64
	v_mul_f32_e32 v76, v73, v72
	v_fma_f32 v77, -v69, v76, v73
	v_fmac_f32_e32 v76, v77, v72
	v_fma_f32 v69, -v69, v76, v73
	v_div_fmas_f32 v69, v69, v72, v76
	v_add_f32_e32 v72, v114, v115
	v_add_f32_e32 v66, v72, v66
	v_add_f32_e32 v66, v66, v67
	v_div_fixup_f32 v64, v69, v68, v64
	v_add_f32_e32 v66, v66, v74
	v_pk_mul_f32 v[68:69], v[64:65], v[64:65]
	v_add_f32_e32 v66, v66, v75
	v_add_f32_e32 v66, v66, v68
	v_add_f32_e32 v66, v66, v69
	s_nop 1
	s_waitcnt lgkmcnt(0)
	v_add_f32_dpp v66, v66, v66 quad_perm:[1,0,3,2] row_mask:0xf bank_mask:0xf
	s_nop 1
	s_waitcnt lgkmcnt(0)
	v_add_f32_dpp v68, v66, v66 quad_perm:[2,3,0,1] row_mask:0xf bank_mask:0xf
	s_nop 1
	v_add_f32_dpp v69, v68, v68 row_half_mirror row_mask:0xf bank_mask:0xf
	v_ashrrev_i32_e32 v67, 3, v126
	v_cmp_gt_i32_e32 vcc, 8, v67
	v_mov_b32_e32 v66, 1.0
	s_and_saveexec_b64 s[0:1], vcc
	s_cbranch_execz .LBB0_328
	s_waitcnt lgkmcnt(0)
	v_mov_b32_e32 v66, v69
	v_add_f32_e32 v66, 0x358637bd, v66
	v_mul_f32_e32 v68, 0x4b800000, v66
	v_cmp_gt_f32_e32 vcc, s58, v66
	s_nop 1
	v_cndmask_b32_e32 v66, v66, v68, vcc
	v_rsq_f32_e32 v66, v66
	s_nop 0
	v_mul_f32_e32 v68, 0x45800000, v66
	v_cndmask_b32_e32 v66, v66, v68, vcc
	v_cmp_gt_i32_e32 vcc, 4, v67
	s_nop 1
	v_cndmask_b32_e32 v67, 1.0, v214, vcc
	v_mul_f32_e32 v66, v67, v66
.LBB0_328:
	s_or_b64 exec, exec, s[0:1]
	s_waitcnt lgkmcnt(0)
	v_pk_mul_f32 v[68:69], v[112:113], v[66:67] op_sel_hi:[1,0]
	v_pk_mul_f32 v[72:73], v[62:63], v[66:67] op_sel_hi:[1,0]
	v_pk_mul_f32 v[70:71], v[70:71], v[66:67] op_sel_hi:[1,0]
	v_pk_mul_f32 v[66:67], v[64:65], v[66:67] op_sel_hi:[1,0]
	s_movk_i32 s0, 0x600
	v_cvt_pk_bf16_f32 v65, v66, v67
	v_mov_b64_e32 v[66:67], s[64:65]
	v_mad_i64_i32 v[66:67], s[0:1], v125, s0, v[66:67]
	v_cvt_pk_bf16_f32 v62, v68, v69
	v_cvt_pk_bf16_f32 v63, v72, v73
	v_cvt_pk_bf16_f32 v64, v70, v71
	v_lshl_add_u64 v[66:67], v[110:111], 1, v[66:67]
	global_store_dwordx4 v[66:67], v[62:65], off
	v_lshl_add_u32 v78, v108, 2, s88
	ds_read_b128 v[66:69], v78
	ds_read_b128 v[62:65], v78 offset:16
	v_lshlrev_b32_e32 v70, 16, v42
	v_and_b32_e32 v71, 0xffff0000, v42
	v_lshlrev_b32_e32 v74, 16, v50
	s_waitcnt lgkmcnt(1)
	v_pk_fma_f32 v[66:67], v[66:67], v[70:71], 0 op_sel_hi:[1,1,0]
	ds_read_b128 v[70:73], v78 offset:3072
	v_and_b32_e32 v75, 0xffff0000, v50
	ds_read_b128 v[84:87], v78 offset:9216
	ds_read_b128 v[88:91], v78 offset:12288
	s_waitcnt lgkmcnt(2)
	v_pk_fma_f32 v[66:67], v[70:71], v[74:75], v[66:67]
	ds_read_b128 v[74:77], v78 offset:6144
	v_lshlrev_b32_e32 v70, 16, v46
	v_and_b32_e32 v71, 0xffff0000, v46
	s_waitcnt lgkmcnt(0)
; DI float siluf(float x) { return x / (1.f + __expf(-x)); }
; DI void prep_dn(const Params& p, int layer, int tile, char* lds) {
;     ...
;       for (int j = 0; j < 5; ++j) {
;         float x[8];
;         unpack8(xr[u][j], x);
;         const float4 w0 = *(const float4*)(cw + j * 768 + ch8 * 8), w1 = *(const float4*)(cw + j * 768 + ch8 * 8 + 4);
;         acc[0] += x[0] * w0.x; acc[1] += x[1] * w0.y; acc[2] += x[2] * w0.z; acc[3] += x[3] * w0.w;
;         acc[4] += x[4] * w1.x; acc[5] += x[5] * w1.y; acc[6] += x[6] * w1.z; acc[7] += x[7] * w1.w;
;       }
;       float ss = 0.f;
; #pragma unroll
;       for (int e = 0; e < 8; ++e) { acc[e] = siluf(acc[e]); ss += acc[e] * acc[e]; }
;       ss += __shfl_xor(ss, 1); ss += __shfl_xor(ss, 2); ss += __shfl_xor(ss, 4);
;       const int grp = ch8 >> 3;
;       const float sc = grp < 8 ? rsqrtf(ss + 1e-6f) * (grp < 4 ? 0.125f : 1.f) : 1.f;
	v_pk_fma_f32 v[66:67], v[74:75], v[70:71], v[66:67]
	v_lshlrev_b32_e32 v70, 16, v58
	v_and_b32_e32 v71, 0xffff0000, v58
	v_pk_fma_f32 v[66:67], v[84:85], v[70:71], v[66:67]
	v_lshlrev_b32_e32 v70, 16, v54
	v_and_b32_e32 v71, 0xffff0000, v54
	v_pk_fma_f32 v[66:67], v[88:89], v[70:71], v[66:67]
	s_nop 0
	v_mul_f32_e32 v42, 0xbfb8aa3b, v66
	v_exp_f32_e32 v70, v42
	v_mul_f32_e32 v42, 0xbfb8aa3b, v67
	v_exp_f32_e32 v71, v42
	s_nop 0
	v_pk_add_f32 v[70:71], v[70:71], 1.0 op_sel_hi:[1,0]
	s_nop 0
	v_div_scale_f32 v42, s[0:1], v71, v71, v67
	v_rcp_f32_e32 v46, v42
	s_nop 0
	v_fma_f32 v50, -v42, v46, 1.0
	v_fmac_f32_e32 v46, v50, v46
	v_div_scale_f32 v50, vcc, v67, v71, v67
	v_mul_f32_e32 v54, v50, v46
	v_fma_f32 v58, -v42, v54, v50
	v_fmac_f32_e32 v54, v58, v46
	v_fma_f32 v42, -v42, v54, v50
	v_div_fmas_f32 v42, v42, v46, v54
	v_div_fixup_f32 v83, v42, v71, v67
	v_div_scale_f32 v42, s[0:1], v70, v70, v66
	v_rcp_f32_e32 v46, v42
	s_nop 0
	v_fma_f32 v50, -v42, v46, 1.0
	v_fmac_f32_e32 v46, v50, v46
	v_div_scale_f32 v50, vcc, v66, v70, v66
	v_mul_f32_e32 v54, v50, v46
	v_fma_f32 v58, -v42, v54, v50
	v_fmac_f32_e32 v54, v58, v46
	v_fma_f32 v42, -v42, v54, v50
	v_div_fmas_f32 v42, v42, v46, v54
	v_div_fixup_f32 v82, v42, v70, v66
	v_lshlrev_b32_e32 v42, 16, v43
	v_and_b32_e32 v43, 0xffff0000, v43
	v_pk_fma_f32 v[42:43], v[68:69], v[42:43], 0 op_sel_hi:[1,1,0]
	v_lshlrev_b32_e32 v50, 16, v51
	v_and_b32_e32 v51, 0xffff0000, v51
	v_pk_fma_f32 v[42:43], v[72:73], v[50:51], v[42:43]
	v_lshlrev_b32_e32 v46, 16, v47
	v_and_b32_e32 v47, 0xffff0000, v47
	v_pk_fma_f32 v[42:43], v[76:77], v[46:47], v[42:43]
	v_lshlrev_b32_e32 v46, 16, v59
	v_and_b32_e32 v47, 0xffff0000, v59
	v_pk_fma_f32 v[42:43], v[86:87], v[46:47], v[42:43]
	v_lshlrev_b32_e32 v46, 16, v55
	v_and_b32_e32 v47, 0xffff0000, v55
	v_pk_fma_f32 v[42:43], v[90:91], v[46:47], v[42:43]
	ds_read_b128 v[66:69], v78 offset:3088
	v_mul_f32_e32 v46, 0xbfb8aa3b, v42
	v_mul_f32_e32 v47, 0xbfb8aa3b, v43
	v_exp_f32_e32 v46, v46
	v_exp_f32_e32 v47, v47
	ds_read_b128 v[70:73], v78 offset:6160
	ds_read_b128 v[74:77], v78 offset:9232
	ds_read_b128 v[78:81], v78 offset:12304
	v_pk_add_f32 v[46:47], v[46:47], 1.0 op_sel_hi:[1,0]
	v_pk_mul_f32 v[84:85], v[82:83], v[82:83]
	v_div_scale_f32 v50, s[0:1], v47, v47, v43
	v_rcp_f32_e32 v51, v50
	s_nop 0
	v_fma_f32 v54, -v50, v51, 1.0
	v_fmac_f32_e32 v51, v54, v51
	v_div_scale_f32 v54, vcc, v43, v47, v43
	v_mul_f32_e32 v55, v54, v51
	v_fma_f32 v58, -v50, v55, v54
	v_fmac_f32_e32 v55, v58, v51
	v_fma_f32 v50, -v50, v55, v54
	v_div_fmas_f32 v50, v50, v51, v55
	v_div_fixup_f32 v43, v50, v47, v43
	v_div_scale_f32 v47, s[0:1], v46, v46, v42
	v_rcp_f32_e32 v50, v47
	s_nop 0
	v_fma_f32 v51, -v47, v50, 1.0
	v_fmac_f32_e32 v50, v51, v50
	v_div_scale_f32 v51, vcc, v42, v46, v42
	v_mul_f32_e32 v54, v51, v50
	v_fma_f32 v55, -v47, v54, v51
	v_fmac_f32_e32 v54, v55, v50
	v_fma_f32 v47, -v47, v54, v51
	v_div_fmas_f32 v47, v47, v50, v54
	v_lshlrev_b32_e32 v50, 16, v44
	v_and_b32_e32 v51, 0xffff0000, v44
	v_pk_fma_f32 v[50:51], v[62:63], v[50:51], 0 op_sel_hi:[1,1,0]
	v_lshlrev_b32_e32 v54, 16, v52
	v_and_b32_e32 v55, 0xffff0000, v52
	s_waitcnt lgkmcnt(3)
	v_pk_fma_f32 v[50:51], v[66:67], v[54:55], v[50:51]
	v_lshlrev_b32_e32 v54, 16, v48
	v_and_b32_e32 v55, 0xffff0000, v48
	s_waitcnt lgkmcnt(2)
	v_pk_fma_f32 v[50:51], v[70:71], v[54:55], v[50:51]
	v_lshlrev_b32_e32 v54, 16, v60
	v_and_b32_e32 v55, 0xffff0000, v60
	s_waitcnt lgkmcnt(1)
	v_pk_fma_f32 v[50:51], v[74:75], v[54:55], v[50:51]
	v_lshlrev_b32_e32 v54, 16, v56
	v_and_b32_e32 v55, 0xffff0000, v56
	s_waitcnt lgkmcnt(0)
	v_pk_fma_f32 v[50:51], v[78:79], v[54:55], v[50:51]
	v_div_fixup_f32 v42, v47, v46, v42
	v_mul_f32_e32 v44, 0xbfb8aa3b, v50
	v_exp_f32_e32 v54, v44
	v_mul_f32_e32 v44, 0xbfb8aa3b, v51
	v_exp_f32_e32 v55, v44
	v_pk_mul_f32 v[46:47], v[42:43], v[42:43]
	v_pk_add_f32 v[54:55], v[54:55], 1.0 op_sel_hi:[1,0]
	s_nop 0
	v_div_scale_f32 v44, s[0:1], v55, v55, v51
	v_rcp_f32_e32 v48, v44
	s_nop 0
	v_fma_f32 v52, -v44, v48, 1.0
	v_fmac_f32_e32 v48, v52, v48
	v_div_scale_f32 v52, vcc, v51, v55, v51
	v_mul_f32_e32 v56, v52, v48
	v_fma_f32 v58, -v44, v56, v52
	v_fmac_f32_e32 v56, v58, v48
	v_fma_f32 v44, -v44, v56, v52
	v_div_fmas_f32 v44, v44, v48, v56
	v_div_fixup_f32 v51, v44, v55, v51
	v_div_scale_f32 v44, s[0:1], v54, v54, v50
	v_rcp_f32_e32 v48, v44
	s_nop 0
	v_fma_f32 v52, -v44, v48, 1.0
	v_fmac_f32_e32 v48, v52, v48
	v_div_scale_f32 v52, vcc, v50, v54, v50
	v_mul_f32_e32 v55, v52, v48
	v_fma_f32 v56, -v44, v55, v52
	v_fmac_f32_e32 v55, v56, v48
	v_fma_f32 v44, -v44, v55, v52
	v_div_fmas_f32 v44, v44, v48, v55
	v_div_fixup_f32 v50, v44, v54, v50
	v_lshlrev_b32_e32 v44, 16, v45
	v_and_b32_e32 v45, 0xffff0000, v45
	v_pk_fma_f32 v[44:45], v[64:65], v[44:45], 0 op_sel_hi:[1,1,0]
	v_lshlrev_b32_e32 v52, 16, v53
	v_and_b32_e32 v53, 0xffff0000, v53
	v_pk_fma_f32 v[44:45], v[68:69], v[52:53], v[44:45]
	v_lshlrev_b32_e32 v48, 16, v49
	v_and_b32_e32 v49, 0xffff0000, v49
	v_pk_fma_f32 v[44:45], v[72:73], v[48:49], v[44:45]
	v_lshlrev_b32_e32 v48, 16, v61
	v_and_b32_e32 v49, 0xffff0000, v61
	v_pk_fma_f32 v[44:45], v[76:77], v[48:49], v[44:45]
	v_lshlrev_b32_e32 v48, 16, v57
	v_and_b32_e32 v49, 0xffff0000, v57
	v_pk_fma_f32 v[44:45], v[80:81], v[48:49], v[44:45]
	v_pk_mul_f32 v[54:55], v[50:51], v[50:51]
	v_mul_f32_e32 v48, 0xbfb8aa3b, v44
	v_mul_f32_e32 v49, 0xbfb8aa3b, v45
	v_exp_f32_e32 v48, v48
	v_exp_f32_e32 v49, v49
	s_nop 0
	v_pk_add_f32 v[48:49], v[48:49], 1.0 op_sel_hi:[1,0]
	s_nop 0
	v_div_scale_f32 v52, s[0:1], v49, v49, v45
	v_rcp_f32_e32 v53, v52
	s_nop 0
	v_fma_f32 v56, -v52, v53, 1.0
	v_fmac_f32_e32 v53, v56, v53
	v_div_scale_f32 v56, vcc, v45, v49, v45
	v_mul_f32_e32 v57, v56, v53
	v_fma_f32 v58, -v52, v57, v56
	v_fmac_f32_e32 v57, v58, v53
	v_fma_f32 v52, -v52, v57, v56
	v_div_fmas_f32 v52, v52, v53, v57
	v_div_fixup_f32 v45, v52, v49, v45
	v_div_scale_f32 v49, s[0:1], v48, v48, v44
	v_rcp_f32_e32 v52, v49
	s_nop 0
	v_fma_f32 v53, -v49, v52, 1.0
	v_fmac_f32_e32 v52, v53, v52
	v_div_scale_f32 v53, vcc, v44, v48, v44
	v_mul_f32_e32 v56, v53, v52
	v_fma_f32 v57, -v49, v56, v53
	v_fmac_f32_e32 v56, v57, v52
	v_fma_f32 v49, -v49, v56, v53
	v_div_fmas_f32 v49, v49, v52, v56
	v_add_f32_e32 v52, v84, v85
	v_add_f32_e32 v46, v52, v46
	v_add_f32_e32 v46, v46, v47
	v_div_fixup_f32 v44, v49, v48, v44
	v_add_f32_e32 v46, v46, v54
	v_pk_mul_f32 v[48:49], v[44:45], v[44:45]
	v_add_f32_e32 v46, v46, v55
	v_add_f32_e32 v46, v46, v48
	v_add_f32_e32 v46, v46, v49
	s_nop 1
	s_waitcnt lgkmcnt(0)
	v_add_f32_dpp v46, v46, v46 quad_perm:[1,0,3,2] row_mask:0xf bank_mask:0xf
	s_nop 1
	s_waitcnt lgkmcnt(0)
	v_add_f32_dpp v47, v46, v46 quad_perm:[2,3,0,1] row_mask:0xf bank_mask:0xf
	s_nop 1
	v_add_f32_dpp v48, v47, v47 row_half_mirror row_mask:0xf bank_mask:0xf
	v_ashrrev_i32_e32 v46, 3, v124
	v_cmp_gt_i32_e32 vcc, 8, v46
	s_and_saveexec_b64 s[0:1], vcc
	s_cbranch_execz .LBB0_330
; DI float siluf(float x) { return x / (1.f + __expf(-x)); }
; DI void prep_dn(const Params& p, int layer, int tile, char* lds) {
;     ...
;       for (int j = 0; j < 5; ++j) {
;         float x[8];
;         unpack8(xr[u][j], x);
;         const float4 w0 = *(const float4*)(cw + j * 768 + ch8 * 8), w1 = *(const float4*)(cw + j * 768 + ch8 * 8 + 4);
;         acc[0] += x[0] * w0.x; acc[1] += x[1] * w0.y; acc[2] += x[2] * w0.z; acc[3] += x[3] * w0.w;
;         acc[4] += x[4] * w1.x; acc[5] += x[5] * w1.y; acc[6] += x[6] * w1.z; acc[7] += x[7] * w1.w;
;       }
;       float ss = 0.f;
; #pragma unroll
;       for (int e = 0; e < 8; ++e) { acc[e] = siluf(acc[e]); ss += acc[e] * acc[e]; }
;       ss += __shfl_xor(ss, 1); ss += __shfl_xor(ss, 2); ss += __shfl_xor(ss, 4);
;       const int grp = ch8 >> 3;
;       const float sc = grp < 8 ? rsqrtf(ss + 1e-6f) * (grp < 4 ? 0.125f : 1.f) : 1.f;
; #pragma unroll
;       for (int e = 0; e < 8; ++e) acc[e] *= sc;
;       *(u32x4*)(QKVB + (size_t)row * 768 + ch8 * 8) = pack8(acc);
	s_waitcnt lgkmcnt(0)
	v_mov_b32_e32 v0, v48
	v_add_f32_e32 v0, 0x358637bd, v0
	v_mul_f32_e32 v47, 0x4b800000, v0
	v_cmp_gt_f32_e32 vcc, s58, v0
	s_nop 1
	v_cndmask_b32_e32 v0, v0, v47, vcc
	v_rsq_f32_e32 v0, v0
	s_nop 0
	v_mul_f32_e32 v47, 0x45800000, v0
	v_cndmask_b32_e32 v0, v0, v47, vcc
	v_cmp_gt_i32_e32 vcc, 4, v46
	s_nop 1
	v_cndmask_b32_e32 v46, 1.0, v214, vcc
	v_mul_f32_e32 v0, v46, v0
.LBB0_330:
	s_or_b64 exec, exec, s[0:1]
	v_pk_mul_f32 v[46:47], v[82:83], v[0:1] op_sel_hi:[1,0]
	s_waitcnt lgkmcnt(0)
	v_pk_mul_f32 v[48:49], v[42:43], v[0:1] op_sel_hi:[1,0]
	v_cvt_pk_bf16_f32 v42, v46, v47
	v_mov_b64_e32 v[46:47], s[64:65]
	s_movk_i32 s0, 0x600
	v_pk_mul_f32 v[50:51], v[50:51], v[0:1] op_sel_hi:[1,0]
	v_pk_mul_f32 v[52:53], v[44:45], v[0:1] op_sel_hi:[1,0]
	v_mad_i64_i32 v[46:47], s[0:1], v123, s0, v[46:47]
	v_cvt_pk_bf16_f32 v43, v48, v49
	v_cvt_pk_bf16_f32 v44, v50, v51
	v_cvt_pk_bf16_f32 v45, v52, v53
	v_lshl_add_u64 v[46:47], v[108:109], 1, v[46:47]
	global_store_dwordx4 v[46:47], v[42:45], off
	v_lshl_add_u32 v58, v106, 2, s88
	ds_read_b128 v[46:49], v58
	ds_read_b128 v[42:45], v58 offset:16
	v_lshlrev_b32_e32 v50, 16, v26
	v_and_b32_e32 v51, 0xffff0000, v26
	v_lshlrev_b32_e32 v54, 16, v22
	s_waitcnt lgkmcnt(1)
	v_pk_fma_f32 v[46:47], v[46:47], v[50:51], 0 op_sel_hi:[1,1,0]
	ds_read_b128 v[50:53], v58 offset:3072
	v_and_b32_e32 v55, 0xffff0000, v22
	ds_read_b128 v[64:67], v58 offset:9216
	ds_read_b128 v[68:71], v58 offset:12288
	s_waitcnt lgkmcnt(2)
	v_pk_fma_f32 v[46:47], v[50:51], v[54:55], v[46:47]
	ds_read_b128 v[54:57], v58 offset:6144
	v_lshlrev_b32_e32 v50, 16, v34
	v_and_b32_e32 v51, 0xffff0000, v34
	s_waitcnt lgkmcnt(0)
	v_pk_fma_f32 v[46:47], v[54:55], v[50:51], v[46:47]
	v_lshlrev_b32_e32 v50, 16, v30
	v_and_b32_e32 v51, 0xffff0000, v30
	v_pk_fma_f32 v[46:47], v[64:65], v[50:51], v[46:47]
	v_lshlrev_b32_e32 v50, 16, v38
	v_and_b32_e32 v51, 0xffff0000, v38
	v_pk_fma_f32 v[46:47], v[68:69], v[50:51], v[46:47]
	s_nop 0
	v_mul_f32_e32 v0, 0xbfb8aa3b, v46
	v_exp_f32_e32 v50, v0
	v_mul_f32_e32 v0, 0xbfb8aa3b, v47
	v_exp_f32_e32 v51, v0
	v_mov_b32_e32 v0, 1.0
	v_pk_add_f32 v[50:51], v[50:51], 1.0 op_sel_hi:[1,0]
	s_nop 0
	v_div_scale_f32 v22, s[0:1], v51, v51, v47
	v_rcp_f32_e32 v26, v22
	s_nop 0
	v_fma_f32 v30, -v22, v26, 1.0
	v_fmac_f32_e32 v26, v30, v26
	v_div_scale_f32 v30, vcc, v47, v51, v47
	v_mul_f32_e32 v34, v30, v26
	v_fma_f32 v38, -v22, v34, v30
	v_fmac_f32_e32 v34, v38, v26
	v_fma_f32 v22, -v22, v34, v30
	v_div_fmas_f32 v22, v22, v26, v34
	v_div_fixup_f32 v63, v22, v51, v47
	v_div_scale_f32 v22, s[0:1], v50, v50, v46
	v_rcp_f32_e32 v26, v22
	s_nop 0
	v_fma_f32 v30, -v22, v26, 1.0
	v_fmac_f32_e32 v26, v30, v26
	v_div_scale_f32 v30, vcc, v46, v50, v46
	v_mul_f32_e32 v34, v30, v26
	v_fma_f32 v38, -v22, v34, v30
	v_fmac_f32_e32 v34, v38, v26
	v_fma_f32 v22, -v22, v34, v30
	v_div_fmas_f32 v22, v22, v26, v34
	v_lshlrev_b32_e32 v26, 16, v27
	v_and_b32_e32 v27, 0xffff0000, v27
	v_div_fixup_f32 v62, v22, v50, v46
	v_pk_fma_f32 v[26:27], v[48:49], v[26:27], 0 op_sel_hi:[1,1,0]
	v_lshlrev_b32_e32 v22, 16, v23
	v_and_b32_e32 v23, 0xffff0000, v23
	v_pk_fma_f32 v[22:23], v[52:53], v[22:23], v[26:27]
	v_lshlrev_b32_e32 v26, 16, v35
	v_and_b32_e32 v27, 0xffff0000, v35
	v_pk_fma_f32 v[22:23], v[56:57], v[26:27], v[22:23]
	v_lshlrev_b32_e32 v26, 16, v31
	v_and_b32_e32 v27, 0xffff0000, v31
	v_pk_fma_f32 v[22:23], v[66:67], v[26:27], v[22:23]
	v_lshlrev_b32_e32 v26, 16, v39
	v_and_b32_e32 v27, 0xffff0000, v39
	v_pk_fma_f32 v[22:23], v[70:71], v[26:27], v[22:23]
	ds_read_b128 v[46:49], v58 offset:3088
	v_mul_f32_e32 v26, 0xbfb8aa3b, v22
	v_mul_f32_e32 v27, 0xbfb8aa3b, v23
	v_exp_f32_e32 v26, v26
	v_exp_f32_e32 v27, v27
	ds_read_b128 v[50:53], v58 offset:6160
	ds_read_b128 v[54:57], v58 offset:9232
	ds_read_b128 v[58:61], v58 offset:12304
	v_pk_add_f32 v[26:27], v[26:27], 1.0 op_sel_hi:[1,0]
	v_pk_mul_f32 v[64:65], v[62:63], v[62:63]
	v_div_scale_f32 v30, s[0:1], v27, v27, v23
	v_rcp_f32_e32 v31, v30
	s_nop 0
	v_fma_f32 v34, -v30, v31, 1.0
	v_fmac_f32_e32 v31, v34, v31
	v_div_scale_f32 v34, vcc, v23, v27, v23
	v_mul_f32_e32 v35, v34, v31
	v_fma_f32 v38, -v30, v35, v34
	v_fmac_f32_e32 v35, v38, v31
	v_fma_f32 v30, -v30, v35, v34
	v_div_fmas_f32 v30, v30, v31, v35
	v_div_fixup_f32 v23, v30, v27, v23
	v_div_scale_f32 v27, s[0:1], v26, v26, v22
	v_rcp_f32_e32 v30, v27
	s_nop 0
	v_fma_f32 v31, -v27, v30, 1.0
	v_fmac_f32_e32 v30, v31, v30
	v_div_scale_f32 v31, vcc, v22, v26, v22
	v_mul_f32_e32 v34, v31, v30
	v_fma_f32 v35, -v27, v34, v31
	v_fmac_f32_e32 v34, v35, v30
	v_fma_f32 v27, -v27, v34, v31
	v_div_fmas_f32 v27, v27, v30, v34
	v_lshlrev_b32_e32 v30, 16, v28
	v_and_b32_e32 v31, 0xffff0000, v28
	v_pk_fma_f32 v[30:31], v[42:43], v[30:31], 0 op_sel_hi:[1,1,0]
	v_lshlrev_b32_e32 v34, 16, v24
	v_and_b32_e32 v35, 0xffff0000, v24
	s_waitcnt lgkmcnt(3)
	v_pk_fma_f32 v[30:31], v[46:47], v[34:35], v[30:31]
	v_lshlrev_b32_e32 v34, 16, v36
	v_and_b32_e32 v35, 0xffff0000, v36
	s_waitcnt lgkmcnt(2)
	v_pk_fma_f32 v[30:31], v[50:51], v[34:35], v[30:31]
	v_lshlrev_b32_e32 v34, 16, v32
	v_and_b32_e32 v35, 0xffff0000, v32
	s_waitcnt lgkmcnt(1)
	v_pk_fma_f32 v[30:31], v[54:55], v[34:35], v[30:31]
	v_lshlrev_b32_e32 v34, 16, v40
	v_and_b32_e32 v35, 0xffff0000, v40
	s_waitcnt lgkmcnt(0)
; DI float siluf(float x) { return x / (1.f + __expf(-x)); }
; DI void prep_dn(const Params& p, int layer, int tile, char* lds) {
;     ...
;       for (int j = 0; j < 5; ++j) {
;         float x[8];
;         unpack8(xr[u][j], x);
;         const float4 w0 = *(const float4*)(cw + j * 768 + ch8 * 8), w1 = *(const float4*)(cw + j * 768 + ch8 * 8 + 4);
;         acc[0] += x[0] * w0.x; acc[1] += x[1] * w0.y; acc[2] += x[2] * w0.z; acc[3] += x[3] * w0.w;
;         acc[4] += x[4] * w1.x; acc[5] += x[5] * w1.y; acc[6] += x[6] * w1.z; acc[7] += x[7] * w1.w;
;       }
;       float ss = 0.f;
; #pragma unroll
;       for (int e = 0; e < 8; ++e) { acc[e] = siluf(acc[e]); ss += acc[e] * acc[e]; }
;       ss += __shfl_xor(ss, 1); ss += __shfl_xor(ss, 2); ss += __shfl_xor(ss, 4);
;       const int grp = ch8 >> 3;
;       const float sc = grp < 8 ? rsqrtf(ss + 1e-6f) * (grp < 4 ? 0.125f : 1.f) : 1.f;
; #pragma unroll
;       for (int e = 0; e < 8; ++e) acc[e] *= sc;
;       *(u32x4*)(QKVB + (size_t)row * 768 + ch8 * 8) = pack8(acc);
	v_pk_fma_f32 v[30:31], v[58:59], v[34:35], v[30:31]
	v_div_fixup_f32 v22, v27, v26, v22
	v_mul_f32_e32 v24, 0xbfb8aa3b, v30
	v_exp_f32_e32 v34, v24
	v_mul_f32_e32 v24, 0xbfb8aa3b, v31
	v_exp_f32_e32 v35, v24
	v_pk_mul_f32 v[26:27], v[22:23], v[22:23]
	v_pk_add_f32 v[34:35], v[34:35], 1.0 op_sel_hi:[1,0]
	s_nop 0
	v_div_scale_f32 v24, s[0:1], v35, v35, v31
	v_rcp_f32_e32 v28, v24
	s_nop 0
	v_fma_f32 v32, -v24, v28, 1.0
	v_fmac_f32_e32 v28, v32, v28
	v_div_scale_f32 v32, vcc, v31, v35, v31
	v_mul_f32_e32 v36, v32, v28
	v_fma_f32 v38, -v24, v36, v32
	v_fmac_f32_e32 v36, v38, v28
	v_fma_f32 v24, -v24, v36, v32
	v_div_fmas_f32 v24, v24, v28, v36
	v_div_fixup_f32 v31, v24, v35, v31
	v_div_scale_f32 v24, s[0:1], v34, v34, v30
	v_rcp_f32_e32 v28, v24
	s_nop 0
	v_fma_f32 v32, -v24, v28, 1.0
	v_fmac_f32_e32 v28, v32, v28
	v_div_scale_f32 v32, vcc, v30, v34, v30
	v_mul_f32_e32 v35, v32, v28
	v_fma_f32 v36, -v24, v35, v32
	v_fmac_f32_e32 v35, v36, v28
	v_fma_f32 v24, -v24, v35, v32
	v_div_fmas_f32 v24, v24, v28, v35
	v_lshlrev_b32_e32 v28, 16, v29
	v_and_b32_e32 v29, 0xffff0000, v29
	v_div_fixup_f32 v30, v24, v34, v30
	v_pk_fma_f32 v[28:29], v[44:45], v[28:29], 0 op_sel_hi:[1,1,0]
	v_lshlrev_b32_e32 v24, 16, v25
	v_and_b32_e32 v25, 0xffff0000, v25
	v_pk_fma_f32 v[24:25], v[48:49], v[24:25], v[28:29]
	v_lshlrev_b32_e32 v28, 16, v37
	v_and_b32_e32 v29, 0xffff0000, v37
	v_pk_fma_f32 v[24:25], v[52:53], v[28:29], v[24:25]
	v_lshlrev_b32_e32 v28, 16, v33
	v_and_b32_e32 v29, 0xffff0000, v33
	v_pk_fma_f32 v[24:25], v[56:57], v[28:29], v[24:25]
	v_lshlrev_b32_e32 v28, 16, v41
	v_and_b32_e32 v29, 0xffff0000, v41
	v_pk_fma_f32 v[24:25], v[60:61], v[28:29], v[24:25]
	v_pk_mul_f32 v[34:35], v[30:31], v[30:31]
	v_mul_f32_e32 v28, 0xbfb8aa3b, v24
	v_mul_f32_e32 v29, 0xbfb8aa3b, v25
	v_exp_f32_e32 v28, v28
	v_exp_f32_e32 v29, v29
	s_nop 0
	v_pk_add_f32 v[28:29], v[28:29], 1.0 op_sel_hi:[1,0]
	s_nop 0
	v_div_scale_f32 v32, s[0:1], v29, v29, v25
	v_rcp_f32_e32 v33, v32
	s_nop 0
	v_fma_f32 v36, -v32, v33, 1.0
	v_fmac_f32_e32 v33, v36, v33
	v_div_scale_f32 v36, vcc, v25, v29, v25
	v_mul_f32_e32 v37, v36, v33
	v_fma_f32 v38, -v32, v37, v36
	v_fmac_f32_e32 v37, v38, v33
	v_fma_f32 v32, -v32, v37, v36
	v_div_fmas_f32 v32, v32, v33, v37
	v_div_fixup_f32 v25, v32, v29, v25
	v_div_scale_f32 v29, s[0:1], v28, v28, v24
	v_rcp_f32_e32 v32, v29
	s_nop 0
	v_fma_f32 v33, -v29, v32, 1.0
	v_fmac_f32_e32 v32, v33, v32
	v_div_scale_f32 v33, vcc, v24, v28, v24
	v_mul_f32_e32 v36, v33, v32
	v_fma_f32 v37, -v29, v36, v33
	v_fmac_f32_e32 v36, v37, v32
	v_fma_f32 v29, -v29, v36, v33
	v_div_fmas_f32 v29, v29, v32, v36
	v_add_f32_e32 v32, v64, v65
	v_add_f32_e32 v26, v32, v26
	v_add_f32_e32 v26, v26, v27
	v_div_fixup_f32 v24, v29, v28, v24
	v_add_f32_e32 v26, v26, v34
	v_pk_mul_f32 v[28:29], v[24:25], v[24:25]
	v_add_f32_e32 v26, v26, v35
	v_add_f32_e32 v26, v26, v28
	v_add_f32_e32 v26, v26, v29
	s_nop 1
	s_waitcnt lgkmcnt(0)
	v_add_f32_dpp v26, v26, v26 quad_perm:[1,0,3,2] row_mask:0xf bank_mask:0xf
	s_nop 1
	s_waitcnt lgkmcnt(0)
	v_add_f32_dpp v28, v26, v26 quad_perm:[2,3,0,1] row_mask:0xf bank_mask:0xf
	s_nop 1
	v_add_f32_dpp v29, v28, v28 row_half_mirror row_mask:0xf bank_mask:0xf
	v_ashrrev_i32_e32 v27, 3, v122
	v_cmp_gt_i32_e32 vcc, 8, v27
	v_mov_b32_e32 v26, 1.0
	s_and_saveexec_b64 s[0:1], vcc
	s_cbranch_execz .LBB0_332
	s_waitcnt lgkmcnt(0)
	v_mov_b32_e32 v26, v29
	v_add_f32_e32 v26, 0x358637bd, v26
	v_mul_f32_e32 v28, 0x4b800000, v26
	v_cmp_gt_f32_e32 vcc, s58, v26
	s_nop 1
	v_cndmask_b32_e32 v26, v26, v28, vcc
	v_rsq_f32_e32 v26, v26
	s_nop 0
	v_mul_f32_e32 v28, 0x45800000, v26
	v_cndmask_b32_e32 v26, v26, v28, vcc
	v_cmp_gt_i32_e32 vcc, 4, v27
	s_nop 1
	v_cndmask_b32_e32 v27, 1.0, v214, vcc
	v_mul_f32_e32 v26, v27, v26
.LBB0_332:
	s_or_b64 exec, exec, s[0:1]
	s_waitcnt lgkmcnt(0)
	v_pk_mul_f32 v[28:29], v[62:63], v[26:27] op_sel_hi:[1,0]
	v_pk_mul_f32 v[32:33], v[22:23], v[26:27] op_sel_hi:[1,0]
	v_pk_mul_f32 v[30:31], v[30:31], v[26:27] op_sel_hi:[1,0]
	v_pk_mul_f32 v[26:27], v[24:25], v[26:27] op_sel_hi:[1,0]
	s_movk_i32 s0, 0x600
	v_cvt_pk_bf16_f32 v25, v26, v27
	v_mov_b64_e32 v[26:27], s[64:65]
	v_mad_i64_i32 v[26:27], s[0:1], v121, s0, v[26:27]
	v_cvt_pk_bf16_f32 v22, v28, v29
	v_cvt_pk_bf16_f32 v23, v32, v33
	v_cvt_pk_bf16_f32 v24, v30, v31
	v_lshl_add_u64 v[26:27], v[106:107], 1, v[26:27]
	global_store_dwordx4 v[26:27], v[22:25], off
	v_lshl_add_u32 v38, v104, 2, s88
	ds_read_b128 v[26:29], v38
	ds_read_b128 v[22:25], v38 offset:16
	v_lshlrev_b32_e32 v30, 16, v2
	v_and_b32_e32 v31, 0xffff0000, v2
	v_lshlrev_b32_e32 v34, 16, v10
	s_waitcnt lgkmcnt(1)
	v_pk_fma_f32 v[26:27], v[26:27], v[30:31], 0 op_sel_hi:[1,1,0]
	ds_read_b128 v[30:33], v38 offset:3072
	v_and_b32_e32 v35, 0xffff0000, v10
	ds_read_b128 v[44:47], v38 offset:9216
	ds_read_b128 v[48:51], v38 offset:12288
	s_waitcnt lgkmcnt(2)
	v_pk_fma_f32 v[26:27], v[30:31], v[34:35], v[26:27]
	ds_read_b128 v[34:37], v38 offset:6144
	v_lshlrev_b32_e32 v30, 16, v6
	v_and_b32_e32 v31, 0xffff0000, v6
	s_waitcnt lgkmcnt(0)
; DI float siluf(float x) { return x / (1.f + __expf(-x)); }
; DI void prep_dn(const Params& p, int layer, int tile, char* lds) {
;     ...
;       for (int j = 0; j < 5; ++j) {
;         float x[8];
;         unpack8(xr[u][j], x);
;         const float4 w0 = *(const float4*)(cw + j * 768 + ch8 * 8), w1 = *(const float4*)(cw + j * 768 + ch8 * 8 + 4);
;         acc[0] += x[0] * w0.x; acc[1] += x[1] * w0.y; acc[2] += x[2] * w0.z; acc[3] += x[3] * w0.w;
;         acc[4] += x[4] * w1.x; acc[5] += x[5] * w1.y; acc[6] += x[6] * w1.z; acc[7] += x[7] * w1.w;
;       }
;       float ss = 0.f;
; #pragma unroll
;       for (int e = 0; e < 8; ++e) { acc[e] = siluf(acc[e]); ss += acc[e] * acc[e]; }
;       ss += __shfl_xor(ss, 1); ss += __shfl_xor(ss, 2); ss += __shfl_xor(ss, 4);
;       const int grp = ch8 >> 3;
;       const float sc = grp < 8 ? rsqrtf(ss + 1e-6f) * (grp < 4 ? 0.125f : 1.f) : 1.f;
; #pragma unroll
;       for (int e = 0; e < 8; ++e) acc[e] *= sc;
;       *(u32x4*)(QKVB + (size_t)row * 768 + ch8 * 8) = pack8(acc);
	v_pk_fma_f32 v[26:27], v[34:35], v[30:31], v[26:27]
	v_lshlrev_b32_e32 v30, 16, v18
	v_and_b32_e32 v31, 0xffff0000, v18
	v_pk_fma_f32 v[26:27], v[44:45], v[30:31], v[26:27]
	v_lshlrev_b32_e32 v30, 16, v14
	v_and_b32_e32 v31, 0xffff0000, v14
	v_pk_fma_f32 v[26:27], v[48:49], v[30:31], v[26:27]
	s_nop 0
	v_mul_f32_e32 v2, 0xbfb8aa3b, v26
	v_exp_f32_e32 v30, v2
	v_mul_f32_e32 v2, 0xbfb8aa3b, v27
	v_exp_f32_e32 v31, v2
	s_nop 0
	v_pk_add_f32 v[30:31], v[30:31], 1.0 op_sel_hi:[1,0]
	s_nop 0
	v_div_scale_f32 v2, s[0:1], v31, v31, v27
	v_rcp_f32_e32 v6, v2
	s_nop 0
	v_fma_f32 v10, -v2, v6, 1.0
	v_fmac_f32_e32 v6, v10, v6
	v_div_scale_f32 v10, vcc, v27, v31, v27
	v_mul_f32_e32 v14, v10, v6
	v_fma_f32 v18, -v2, v14, v10
	v_fmac_f32_e32 v14, v18, v6
	v_fma_f32 v2, -v2, v14, v10
	v_div_fmas_f32 v2, v2, v6, v14
	v_div_fixup_f32 v43, v2, v31, v27
	v_div_scale_f32 v2, s[0:1], v30, v30, v26
	v_rcp_f32_e32 v6, v2
	s_nop 0
	v_fma_f32 v10, -v2, v6, 1.0
	v_fmac_f32_e32 v6, v10, v6
	v_div_scale_f32 v10, vcc, v26, v30, v26
	v_mul_f32_e32 v14, v10, v6
	v_fma_f32 v18, -v2, v14, v10
	v_fmac_f32_e32 v14, v18, v6
	v_fma_f32 v2, -v2, v14, v10
	v_div_fmas_f32 v2, v2, v6, v14
	v_div_fixup_f32 v42, v2, v30, v26
	v_lshlrev_b32_e32 v2, 16, v3
	v_and_b32_e32 v3, 0xffff0000, v3
	v_pk_fma_f32 v[2:3], v[28:29], v[2:3], 0 op_sel_hi:[1,1,0]
	v_lshlrev_b32_e32 v10, 16, v11
	v_and_b32_e32 v11, 0xffff0000, v11
	v_pk_fma_f32 v[2:3], v[32:33], v[10:11], v[2:3]
	v_lshlrev_b32_e32 v6, 16, v7
	v_and_b32_e32 v7, 0xffff0000, v7
	v_pk_fma_f32 v[2:3], v[36:37], v[6:7], v[2:3]
	v_lshlrev_b32_e32 v6, 16, v19
	v_and_b32_e32 v7, 0xffff0000, v19
	v_pk_fma_f32 v[2:3], v[46:47], v[6:7], v[2:3]
	v_lshlrev_b32_e32 v6, 16, v15
	v_and_b32_e32 v7, 0xffff0000, v15
	v_pk_fma_f32 v[2:3], v[50:51], v[6:7], v[2:3]
	ds_read_b128 v[26:29], v38 offset:3088
	v_mul_f32_e32 v6, 0xbfb8aa3b, v2
	v_mul_f32_e32 v7, 0xbfb8aa3b, v3
	v_exp_f32_e32 v6, v6
	v_exp_f32_e32 v7, v7
	ds_read_b128 v[30:33], v38 offset:6160
	ds_read_b128 v[34:37], v38 offset:9232
	ds_read_b128 v[38:41], v38 offset:12304
	v_pk_add_f32 v[6:7], v[6:7], 1.0 op_sel_hi:[1,0]
	v_pk_mul_f32 v[44:45], v[42:43], v[42:43]
	v_div_scale_f32 v10, s[0:1], v7, v7, v3
	v_rcp_f32_e32 v11, v10
	s_nop 0
	v_fma_f32 v14, -v10, v11, 1.0
	v_fmac_f32_e32 v11, v14, v11
	v_div_scale_f32 v14, vcc, v3, v7, v3
	v_mul_f32_e32 v15, v14, v11
	v_fma_f32 v18, -v10, v15, v14
	v_fmac_f32_e32 v15, v18, v11
	v_fma_f32 v10, -v10, v15, v14
	v_div_fmas_f32 v10, v10, v11, v15
	v_div_fixup_f32 v3, v10, v7, v3
	v_div_scale_f32 v7, s[0:1], v6, v6, v2
	v_rcp_f32_e32 v10, v7
	s_nop 0
	v_fma_f32 v11, -v7, v10, 1.0
	v_fmac_f32_e32 v10, v11, v10
	v_div_scale_f32 v11, vcc, v2, v6, v2
	v_mul_f32_e32 v14, v11, v10
	v_fma_f32 v15, -v7, v14, v11
	v_fmac_f32_e32 v14, v15, v10
	v_fma_f32 v7, -v7, v14, v11
	v_div_fmas_f32 v7, v7, v10, v14
	v_lshlrev_b32_e32 v10, 16, v4
	v_and_b32_e32 v11, 0xffff0000, v4
	v_pk_fma_f32 v[10:11], v[22:23], v[10:11], 0 op_sel_hi:[1,1,0]
	v_lshlrev_b32_e32 v14, 16, v12
	v_and_b32_e32 v15, 0xffff0000, v12
	s_waitcnt lgkmcnt(3)
	v_pk_fma_f32 v[10:11], v[26:27], v[14:15], v[10:11]
	v_lshlrev_b32_e32 v14, 16, v8
	v_and_b32_e32 v15, 0xffff0000, v8
	s_waitcnt lgkmcnt(2)
	v_pk_fma_f32 v[10:11], v[30:31], v[14:15], v[10:11]
	v_lshlrev_b32_e32 v14, 16, v20
	v_and_b32_e32 v15, 0xffff0000, v20
	s_waitcnt lgkmcnt(1)
	v_pk_fma_f32 v[10:11], v[34:35], v[14:15], v[10:11]
	v_lshlrev_b32_e32 v14, 16, v16
	v_and_b32_e32 v15, 0xffff0000, v16
	s_waitcnt lgkmcnt(0)
	v_pk_fma_f32 v[10:11], v[38:39], v[14:15], v[10:11]
	v_div_fixup_f32 v2, v7, v6, v2
	v_mul_f32_e32 v4, 0xbfb8aa3b, v10
	v_exp_f32_e32 v14, v4
	v_mul_f32_e32 v4, 0xbfb8aa3b, v11
	v_exp_f32_e32 v15, v4
	v_pk_mul_f32 v[6:7], v[2:3], v[2:3]
	v_pk_add_f32 v[14:15], v[14:15], 1.0 op_sel_hi:[1,0]
	s_nop 0
	v_div_scale_f32 v4, s[0:1], v15, v15, v11
	v_rcp_f32_e32 v8, v4
	s_nop 0
	v_fma_f32 v12, -v4, v8, 1.0
	v_fmac_f32_e32 v8, v12, v8
	v_div_scale_f32 v12, vcc, v11, v15, v11
	v_mul_f32_e32 v16, v12, v8
	v_fma_f32 v18, -v4, v16, v12
	v_fmac_f32_e32 v16, v18, v8
	v_fma_f32 v4, -v4, v16, v12
	v_div_fmas_f32 v4, v4, v8, v16
	v_div_fixup_f32 v11, v4, v15, v11
	v_div_scale_f32 v4, s[0:1], v14, v14, v10
	v_rcp_f32_e32 v8, v4
	s_nop 0
	v_fma_f32 v12, -v4, v8, 1.0
	v_fmac_f32_e32 v8, v12, v8
	v_div_scale_f32 v12, vcc, v10, v14, v10
	v_mul_f32_e32 v15, v12, v8
	v_fma_f32 v16, -v4, v15, v12
	v_fmac_f32_e32 v15, v16, v8
	v_fma_f32 v4, -v4, v15, v12
	v_div_fmas_f32 v4, v4, v8, v15
	v_div_fixup_f32 v10, v4, v14, v10
	v_lshlrev_b32_e32 v4, 16, v5
	v_and_b32_e32 v5, 0xffff0000, v5
	v_pk_fma_f32 v[4:5], v[24:25], v[4:5], 0 op_sel_hi:[1,1,0]
	v_lshlrev_b32_e32 v12, 16, v13
	v_and_b32_e32 v13, 0xffff0000, v13
	v_pk_fma_f32 v[4:5], v[28:29], v[12:13], v[4:5]
	v_lshlrev_b32_e32 v8, 16, v9
	v_and_b32_e32 v9, 0xffff0000, v9
	v_pk_fma_f32 v[4:5], v[32:33], v[8:9], v[4:5]
	v_lshlrev_b32_e32 v8, 16, v21
	v_and_b32_e32 v9, 0xffff0000, v21
	v_pk_fma_f32 v[4:5], v[36:37], v[8:9], v[4:5]
	v_lshlrev_b32_e32 v8, 16, v17
	v_and_b32_e32 v9, 0xffff0000, v17
	v_pk_fma_f32 v[4:5], v[40:41], v[8:9], v[4:5]
	v_pk_mul_f32 v[14:15], v[10:11], v[10:11]
	v_mul_f32_e32 v8, 0xbfb8aa3b, v4
	v_mul_f32_e32 v9, 0xbfb8aa3b, v5
	v_exp_f32_e32 v8, v8
	v_exp_f32_e32 v9, v9
	s_nop 0
	v_pk_add_f32 v[8:9], v[8:9], 1.0 op_sel_hi:[1,0]
	s_nop 0
	v_div_scale_f32 v12, s[0:1], v9, v9, v5
	v_rcp_f32_e32 v13, v12
	s_nop 0
	v_fma_f32 v16, -v12, v13, 1.0
	v_fmac_f32_e32 v13, v16, v13
	v_div_scale_f32 v16, vcc, v5, v9, v5
	v_mul_f32_e32 v17, v16, v13
	v_fma_f32 v18, -v12, v17, v16
	v_fmac_f32_e32 v17, v18, v13
	v_fma_f32 v12, -v12, v17, v16
	v_div_fmas_f32 v12, v12, v13, v17
	v_div_fixup_f32 v5, v12, v9, v5
	v_div_scale_f32 v9, s[0:1], v8, v8, v4
	v_rcp_f32_e32 v12, v9
	s_nop 0
	v_fma_f32 v13, -v9, v12, 1.0
	v_fmac_f32_e32 v12, v13, v12
	v_div_scale_f32 v13, vcc, v4, v8, v4
	v_mul_f32_e32 v16, v13, v12
	v_fma_f32 v17, -v9, v16, v13
	v_fmac_f32_e32 v16, v17, v12
	v_fma_f32 v9, -v9, v16, v13
	v_div_fmas_f32 v9, v9, v12, v16
	v_add_f32_e32 v12, v44, v45
	v_add_f32_e32 v6, v12, v6
	v_add_f32_e32 v6, v6, v7
	v_div_fixup_f32 v4, v9, v8, v4
	v_add_f32_e32 v6, v6, v14
	v_pk_mul_f32 v[8:9], v[4:5], v[4:5]
	v_add_f32_e32 v6, v6, v15
	v_add_f32_e32 v6, v6, v8
	v_add_f32_e32 v6, v6, v9
	s_nop 1
	s_waitcnt lgkmcnt(0)
	v_add_f32_dpp v6, v6, v6 quad_perm:[1,0,3,2] row_mask:0xf bank_mask:0xf
	s_nop 1
	s_waitcnt lgkmcnt(0)
	v_add_f32_dpp v7, v6, v6 quad_perm:[2,3,0,1] row_mask:0xf bank_mask:0xf
	s_nop 1
	v_add_f32_dpp v8, v7, v7 row_half_mirror row_mask:0xf bank_mask:0xf
	v_ashrrev_i32_e32 v6, 3, v120
	v_cmp_gt_i32_e32 vcc, 8, v6
	s_and_saveexec_b64 s[0:1], vcc
	s_cbranch_execz .LBB0_285
	s_waitcnt lgkmcnt(0)
	v_mov_b32_e32 v0, v8
	v_add_f32_e32 v0, 0x358637bd, v0
	v_mul_f32_e32 v7, 0x4b800000, v0
	v_cmp_gt_f32_e32 vcc, s58, v0
	s_nop 1
	v_cndmask_b32_e32 v0, v0, v7, vcc
	v_rsq_f32_e32 v0, v0
	s_nop 0
	v_mul_f32_e32 v7, 0x45800000, v0
	v_cndmask_b32_e32 v0, v0, v7, vcc
	v_cmp_gt_i32_e32 vcc, 4, v6
	s_nop 1
	v_cndmask_b32_e32 v6, 1.0, v214, vcc
	v_mul_f32_e32 v0, v6, v0
	s_branch .LBB0_285
